# attA: softmax exponent reference fixed at the per-row score bound (no rescaling; running max kept only for the exact skip / exit tests), first exp group and V^T reads moved under the QK chains, row ma
# baseline (speedup 1.0000x reference)
; #define LAS __attribute__((address_space(3)))
; __device__ __forceinline__ void unit(LAS unsigned char* lds, bf16_t* P1, const bf16_t* vaT, int b, int h, int qblk, float lam, const float* subln_w, const float* khalf) {
;     ...
;         { const bool done = __all(qbound + sl2 * (float)(64 * j + 63 - qrow) < m - 24.f);
;           if (lane == 0) dflag[(jj & 1) * 8 + wid] = done ? 1 : 0; }
;         if (jj + 2 < NT) asm volatile("s_waitcnt vmcnt(8) lgkmcnt(0)\n\ts_barrier" ::: "memory"); else if (jj + 1 < NT) asm volatile("s_waitcnt vmcnt(4) lgkmcnt(0)\n\ts_barrier" ::: "memory"); else asm volatile("s_waitcnt vmcnt(0) lgkmcnt(0)\n\ts_barrier" ::: "memory");
;         { typedef int i32x4 __attribute__((ext_vector_type(4)));
;           const i32x4 fa = *(const LAS i32x4*)(lds + 4 * STG + (jj & 1) * 32), fb = *(const LAS i32x4*)(lds + 4 * STG + (jj & 1) * 32 + 16);
;           if (((fa[0] + fa[1]) + (fa[2] + fa[3])) + ((fb[0] + fb[1]) + (fb[2] + fb[3])) == 8) break; }
.La_flag_done0:
	s_or_b64 exec, exec, s[4:5]
	s_cmp_gt_u32 s73, 2
	s_cbranch_scc0 .La_w00
	s_waitcnt vmcnt(4) lgkmcnt(0)
	s_barrier
	s_branch .La_after_bar0

; #define LAS __attribute__((address_space(3)))
; __device__ __forceinline__ int crow(int r, int hi) { return (r & 3) + 8 * (r >> 2) + 4 * hi; }
; __device__ __forceinline__ void unit(LAS unsigned char* lds, bf16_t* P1, const bf16_t* vaT, int b, int h, int qblk, float lam, const float* subln_w, const float* khalf) {
;     ...
;         if (jj + 2 < NT) asm volatile("s_waitcnt vmcnt(8) lgkmcnt(0)\n\ts_barrier" ::: "memory"); else if (jj + 1 < NT) asm volatile("s_waitcnt vmcnt(4) lgkmcnt(0)\n\ts_barrier" ::: "memory"); else asm volatile("s_waitcnt vmcnt(0) lgkmcnt(0)\n\ts_barrier" ::: "memory");
;         { typedef int i32x4 __attribute__((ext_vector_type(4)));
;           const i32x4 fa = *(const LAS i32x4*)(lds + 4 * STG + (jj & 1) * 32), fb = *(const LAS i32x4*)(lds + 4 * STG + (jj & 1) * 32 + 16);
;           if (((fa[0] + fa[1]) + (fa[2] + fa[3])) + ((fb[0] + fb[1]) + (fb[2] + fb[3])) == 8) break; }
;         if (jj + 3 < NT) { DMA_TILE(j - 3, (stg + 3) & 3); }
;         const LAS unsigned char* kb = lds + stg * STG;
;         stg = (stg + 1) & 3;
;         f32x16 S0, S1;
;         { float slv = sl2; asm volatile("" : "+v"(slv));
; #pragma unroll
;           for (int r = 0; r < 16; ++r) { S0[r] = __builtin_fmaf(slv, (float)((r & 3) + 8 * (r >> 2)), sl2h); S1[r] = S0[r]; } }
; #pragma unroll
;         for (int ks = 0; ks < 4; ++ks) {
;             const bf16x8 a0 = *(const LAS bf16x8*)(kb + koff[ks]);
;             const bf16x8 a1 = *(const LAS bf16x8*)(kb + koff[ks] + 32 * 256);
;             S0 = MFMA32(a0, qf[ks], S0); S1 = MFMA32(a1, qf[ks], S1);
;         }
;         const int kv0 = 64 * j;
;         if (j >= NT - 2) {
; #pragma unroll
;             for (int r = 0; r < 16; ++r) { const int kv = kv0 + crow(r, hi); if (kv > qrow) S0[r] = -INFINITY; if (kv + 32 > qrow) S1[r] = -INFINITY; }
;         }
;         const float tb0 = sl2 * (float)(kv0 - qrow), tb1 = tb0 + sl2 * 32.f;
;         float mx0 = S0[0], mx1 = S1[0];
; #pragma unroll
;         for (int r = 1; r < 16; ++r) { mx0 = fmaxf(mx0, S0[r]); mx1 = fmaxf(mx1, S1[r]); }
;         float mt = fmaxf(mx0 + tb0, mx1 + tb1); mt = fmaxf(mt, __shfl_xor(mt, 32));
;         const bool skip = __all((mt < m - 24.f) || (mt == -INFINITY));
;         if (!skip) {
;         const float mn = fmaxf(m, mt); const float alpha = ex2(m - mn); m = mn;
.La_after_bar0:
	s_lshl_b32 s82, s80, 15
	s_add_i32 s83, s82, 0x8000
	s_sub_i32 s100, s76, 64
	s_and_b32 s2, s81, 2
	s_lshl_b32 s2, s2, 4
	s_add_i32 s2, s2, 0x20000
	v_mov_b32_e32 v70, s2
	ds_read_b128 v[66:69], v70
	ds_read_b128 v[70:73], v70 offset:16
	v_add3_u32 v201, s82, v129, v151
	v_add3_u32 v135, s82, v185, v151
	v_add3_u32 v249, s82, v186, v151
	v_add3_u32 v254, s82, v187, v151
	ds_read_b128 v[192:195], v201
	ds_read_b128 v[202:205], v135
	ds_read_b128 v[210:213], v249
	ds_read_b128 v[218:221], v254
	ds_read_b128 v[196:199], v201 offset:8192
	ds_read_b128 v[206:209], v135 offset:8192
	ds_read_b128 v[214:217], v249 offset:8192
	ds_read_b128 v[222:225], v254 offset:8192
	s_waitcnt lgkmcnt(8)
	v_add3_u32 v66, v66, v67, v68
	v_add3_u32 v69, v69, v70, v71
	v_add_u32_e32 v72, v72, v73
	v_add3_u32 v66, v66, v69, v72
	v_cmp_eq_u32_e32 vcc, 8, v66
	s_cbranch_vccnz .LBB0_420
	s_waitcnt lgkmcnt(4)
	v_mfma_f32_32x32x16_bf16 v[82:97], v[192:195], v[98:101], v[226:241]
	v_add_u32_e32 v244, s82, v168
	v_add_u32_e32 v245, s82, v169
	v_add_u32_e32 v246, s82, v170
	v_mfma_f32_32x32x16_bf16 v[82:97], v[202:205], v[102:105], v[82:97]
	v_add_u32_e32 v247, s82, v171
	v_add_f32_e32 v143, v133, v121
	v_fma_f32 v251, v127, v137, v188
	v_mfma_f32_32x32x16_bf16 v[82:97], v[210:213], v[106:109], v[82:97]
	v_fma_f32 v142, v127, v137, -v132
	v_max_f32_e32 v143, 0xff7fffff, v143
	v_add_f32_e32 v248, v142, v188
	v_mfma_f32_32x32x16_bf16 v[82:97], v[218:221], v[110:113], v[82:97]
	ds_read_b128 v[192:195], v244 offset:16384
	ds_read_b128 v[202:205], v244 offset:20480
	ds_read_b128 v[210:213], v244 offset:24576
	ds_read_b128 v[218:221], v244 offset:28672
	s_waitcnt lgkmcnt(4)
	v_mfma_f32_32x32x16_bf16 v[66:81], v[196:199], v[98:101], v[226:241]
	v_mfma_f32_32x32x16_bf16 v[66:81], v[206:209], v[102:105], v[66:81]
	v_max3_f32 v0, v82, v83, v84
	v_max3_f32 v0, v0, v85, v86
	v_mfma_f32_32x32x16_bf16 v[66:81], v[214:217], v[106:109], v[66:81]
	v_max3_f32 v0, v0, v87, v88
	v_max3_f32 v0, v0, v89, v90
	v_max3_f32 v0, v0, v91, v92
	v_mfma_f32_32x32x16_bf16 v[66:81], v[222:225], v[110:113], v[66:81]
	v_max3_f32 v0, v0, v93, v94
	v_max3_f32 v0, v0, v95, v96
	v_max_f32_e32 v0, v0, v97
	ds_read_b128 v[196:199], v245 offset:16384
	ds_read_b128 v[206:209], v245 offset:20480
	ds_read_b128 v[214:217], v245 offset:24576
	ds_read_b128 v[222:225], v245 offset:28672
	s_nop 3
	v_add_u32_e32 v243, s76, v189
	v_add_u32_e32 v130, 0x60, v243
	v_add_u32_e32 v131, 64, v243
	v_cmp_le_i32_e32 vcc, v130, v125
	s_nop 6
	v_cndmask_b32_e32 v66, v184, v66, vcc
	v_cmp_lt_i32_e32 vcc, v131, v125
	s_nop 1
	v_cndmask_b32_e32 v83, v184, v83, vcc
	v_cmp_le_i32_e32 vcc, v131, v125
	v_add_u32_e32 v131, 0x61, v243
	s_nop 0
	v_cndmask_b32_e32 v82, v184, v82, vcc
	v_cmp_le_i32_e32 vcc, v131, v125
	v_add_u32_e32 v131, 0x42, v243
	s_nop 0
	v_cndmask_b32_e32 v67, v184, v67, vcc
	v_cmp_le_i32_e32 vcc, v131, v125
	v_add_u32_e32 v131, 0x62, v243
	s_nop 0
	v_cndmask_b32_e32 v84, v184, v84, vcc
	v_cmp_le_i32_e32 vcc, v131, v125
	v_add_u32_e32 v131, 0x43, v243
	s_nop 0
	v_cndmask_b32_e32 v68, v184, v68, vcc
	v_cmp_le_i32_e32 vcc, v131, v125
	v_add_u32_e32 v131, 0x63, v243
	s_nop 0
	v_cndmask_b32_e32 v85, v184, v85, vcc
	v_cmp_le_i32_e32 vcc, v131, v125
	v_add_u32_e32 v131, 0x48, v243
	s_nop 0
	v_cndmask_b32_e32 v69, v184, v69, vcc
	v_cmp_le_i32_e32 vcc, v131, v125
	v_add_u32_e32 v131, 0x68, v243
	s_nop 0
	v_cndmask_b32_e32 v86, v184, v86, vcc
	v_cmp_le_i32_e32 vcc, v131, v125
	v_add_u32_e32 v131, 0x49, v243
	s_nop 0
	v_cndmask_b32_e32 v70, v184, v70, vcc
	v_cmp_le_i32_e32 vcc, v131, v125
	v_add_u32_e32 v131, 0x69, v243
	s_nop 0
	v_cndmask_b32_e32 v87, v184, v87, vcc
	v_cmp_le_i32_e32 vcc, v131, v125
	v_add_u32_e32 v131, 0x4a, v243
	s_nop 0
	v_cndmask_b32_e32 v71, v184, v71, vcc
	v_cmp_le_i32_e32 vcc, v131, v125
	v_add_u32_e32 v131, 0x6a, v243
	s_nop 0
	v_cndmask_b32_e32 v88, v184, v88, vcc
	v_cmp_le_i32_e32 vcc, v131, v125
	v_add_u32_e32 v131, 0x4b, v243
	s_nop 0
	v_cndmask_b32_e32 v72, v184, v72, vcc
	v_cmp_le_i32_e32 vcc, v131, v125
	v_add_u32_e32 v131, 0x6b, v243
	s_nop 0
	v_cndmask_b32_e32 v89, v184, v89, vcc
	v_cmp_le_i32_e32 vcc, v131, v125
	v_add_u32_e32 v131, 0x50, v243
	s_nop 0
	v_cndmask_b32_e32 v73, v184, v73, vcc
	v_cmp_le_i32_e32 vcc, v131, v125
	v_add_u32_e32 v131, 0x70, v243
	s_nop 0
	v_cndmask_b32_e32 v90, v184, v90, vcc
	v_cmp_le_i32_e32 vcc, v131, v125
	v_add_u32_e32 v131, 0x51, v243
	s_nop 0
	v_cndmask_b32_e32 v74, v184, v74, vcc
	v_cmp_le_i32_e32 vcc, v131, v125
	v_add_u32_e32 v131, 0x71, v243
	s_nop 0
	v_cndmask_b32_e32 v91, v184, v91, vcc
	v_cmp_le_i32_e32 vcc, v131, v125
	v_add_u32_e32 v131, 0x52, v243
	s_nop 0
	v_cndmask_b32_e32 v75, v184, v75, vcc
	v_cmp_le_i32_e32 vcc, v131, v125
	v_add_u32_e32 v131, 0x72, v243
	s_nop 0
	v_cndmask_b32_e32 v92, v184, v92, vcc
	v_cmp_le_i32_e32 vcc, v131, v125
	v_add_u32_e32 v131, 0x53, v243
	s_nop 0
	v_cndmask_b32_e32 v76, v184, v76, vcc
	v_cmp_le_i32_e32 vcc, v131, v125
	v_add_u32_e32 v131, 0x73, v243
	s_nop 0
	v_cndmask_b32_e32 v93, v184, v93, vcc
	v_cmp_le_i32_e32 vcc, v131, v125
	v_add_u32_e32 v131, 0x58, v243
	s_nop 0
	v_cndmask_b32_e32 v77, v184, v77, vcc
	v_cmp_le_i32_e32 vcc, v131, v125
	v_add_u32_e32 v131, 0x78, v243
	s_nop 0
	v_cndmask_b32_e32 v94, v184, v94, vcc
	v_cmp_le_i32_e32 vcc, v131, v125
	v_add_u32_e32 v131, 0x59, v243
	s_nop 0
	v_cndmask_b32_e32 v78, v184, v78, vcc
	v_cmp_le_i32_e32 vcc, v131, v125
	v_add_u32_e32 v131, 0x79, v243
	s_nop 0
	v_cndmask_b32_e32 v95, v184, v95, vcc
	v_cmp_le_i32_e32 vcc, v131, v125
	v_add_u32_e32 v131, 0x5a, v243
	s_nop 0
	v_cndmask_b32_e32 v79, v184, v79, vcc
	v_cmp_le_i32_e32 vcc, v131, v125
	v_add_u32_e32 v131, 0x7a, v243
	s_nop 0
	v_cndmask_b32_e32 v96, v184, v96, vcc
	v_cmp_le_i32_e32 vcc, v131, v125
	v_add_u32_e32 v131, 0x5b, v243
	v_add_u32_e32 v243, 0x7b, v243
	v_cndmask_b32_e32 v80, v184, v80, vcc
	v_cmp_le_i32_e32 vcc, v131, v125
	s_nop 1
	v_cndmask_b32_e32 v97, v184, v97, vcc
	v_cmp_le_i32_e32 vcc, v243, v125
	s_nop 1
	v_cndmask_b32_e32 v81, v184, v81, vcc
	v_max3_f32 v0, v82, v83, v84
	v_max3_f32 v0, v0, v85, v86
	v_max3_f32 v0, v0, v87, v88
	v_max3_f32 v0, v0, v89, v90
	v_max3_f32 v0, v0, v91, v92
	v_max3_f32 v0, v0, v93, v94
	v_max3_f32 v0, v0, v95, v96
	v_max_f32_e32 v0, v0, v97
	v_fmac_f32_e32 v0, v127, v137
	s_nop 1
	v_max3_f32 v120, v66, v67, v68
	v_max3_f32 v120, v120, v69, v70
	v_max3_f32 v120, v120, v71, v72
	v_max3_f32 v120, v120, v73, v74
	v_max3_f32 v120, v120, v75, v76
	v_max3_f32 v120, v120, v77, v78
	v_max3_f32 v120, v120, v79, v80
	v_max_f32_e32 v120, v120, v81
	v_add_f32_e32 v120, v251, v120
	v_max_f32_e32 v0, v0, v120
	v_mov_b32_e32 v120, v0
	s_nop 1
	v_permlane32_swap_b32_e32 v0, v120
	v_max_f32_e32 v0, v0, v120
	v_cmp_lt_f32_e32 vcc, v0, v143
	v_max_f32_e32 v133, v133, v0
	v_mov_b32_e32 v255, v0
	s_andn2_b64 s[2:3], exec, vcc
	s_cbranch_scc0 .La_endA0
; __device__ __forceinline__ void unit(LAS unsigned char* lds, bf16_t* P1, const bf16_t* vaT, int b, int h, int qblk, float lam, const float* subln_w, const float* khalf) {
;     ...
;         if (jj + 3 < NT) { DMA_TILE(j - 3, (stg + 3) & 3); }
;         const LAS unsigned char* kb = lds + stg * STG;
;         stg = (stg + 1) & 3;
;         f32x16 S0, S1;
;         { float slv = sl2; asm volatile("" : "+v"(slv));
; #pragma unroll
;           for (int r = 0; r < 16; ++r) { S0[r] = __builtin_fmaf(slv, (float)((r & 3) + 8 * (r >> 2)), sl2h); S1[r] = S0[r]; } }
; #pragma unroll
;         for (int ks = 0; ks < 4; ++ks) {
;             const bf16x8 a0 = *(const LAS bf16x8*)(kb + koff[ks]);
;             const bf16x8 a1 = *(const LAS bf16x8*)(kb + koff[ks] + 32 * 256);
;             S0 = MFMA32(a0, qf[ks], S0); S1 = MFMA32(a1, qf[ks], S1);
;         }
;     ...
;         const float mn = fmaxf(m, mt); const float alpha = ex2(m - mn); m = mn;
;         const float c0 = tb0 - mn, c1 = tb1 - mn;
;         f32x2 ps2 = (f32x2){0.f, 0.f};
; #pragma unroll
;         for (int r = 0; r < 16; r += 2) { f32x2 a = (f32x2){S0[r], S0[r + 1]} + c0, bq = (f32x2){S1[r], S1[r + 1]} + c1;
;             a.x = ex2(a.x); a.y = ex2(a.y); bq.x = ex2(bq.x); bq.y = ex2(bq.y); S0[r] = a.x; S0[r + 1] = a.y; S1[r] = bq.x; S1[r + 1] = bq.y; ps2 = ps2 + a; ps2 = ps2 + bq; }
;         l = l * alpha + (ps2.x + ps2.y);
;         if (__any(alpha != 1.f)) {
; #pragma unroll
;             for (int d = 0; d < 4; ++d) O[d] = O[d] * alpha;
;         }
;         u32x4 pk[2][2];
; #pragma unroll
;         for (int s = 0; s < 2; ++s) {
;             pk[0][s] = (u32x4){cvtpk(S0[8 * s + 0], S0[8 * s + 1]), cvtpk(S0[8 * s + 2], S0[8 * s + 3]), cvtpk(S0[8 * s + 4], S0[8 * s + 5]), cvtpk(S0[8 * s + 6], S0[8 * s + 7])};
;             pk[1][s] = (u32x4){cvtpk(S1[8 * s + 0], S1[8 * s + 1]), cvtpk(S1[8 * s + 2], S1[8 * s + 3]), cvtpk(S1[8 * s + 4], S1[8 * s + 5]), cvtpk(S1[8 * s + 6], S1[8 * s + 7])};
;         }
; #pragma unroll
;         for (int d = 0; d < 4; ++d)
; #pragma unroll
;             for (int t2 = 0; t2 < 2; ++t2)
; #pragma unroll
;                 for (int s = 0; s < 2; ++s) {
;                     const bf16x8 vf = *(const LAS bf16x8*)(kb + voff[2 * t2 + s] + d * 32 * 128);
;                     O[d] = MFMA32(vf, __builtin_bit_cast(bf16x8, pk[t2][s]), O[d]);
;                 }
;         }
	v_pk_add_f32 v[82:83], v[82:83], v[142:143] op_sel_hi:[1,0]
	v_pk_add_f32 v[84:85], v[84:85], v[142:143] op_sel_hi:[1,0]
	v_pk_add_f32 v[86:87], v[86:87], v[142:143] op_sel_hi:[1,0]
	v_pk_add_f32 v[88:89], v[88:89], v[142:143] op_sel_hi:[1,0]
	v_exp_f32_e32 v82, v82
	v_exp_f32_e32 v83, v83
	v_exp_f32_e32 v84, v84
	v_exp_f32_e32 v85, v85
	v_exp_f32_e32 v86, v86
	v_exp_f32_e32 v87, v87
	v_exp_f32_e32 v88, v88
	v_exp_f32_e32 v89, v89
	v_pk_add_f32 v[252:253], v[82:83], v[84:85]
	v_cvt_pk_bf16_f32 v82, v82, v83
	v_cvt_pk_bf16_f32 v83, v84, v85
	v_cvt_pk_bf16_f32 v84, v86, v87
	v_cvt_pk_bf16_f32 v85, v88, v89
	v_pk_add_f32 v[252:253], v[252:253], v[86:87]
	v_pk_add_f32 v[252:253], v[252:253], v[88:89]
	s_waitcnt lgkmcnt(4)
	v_mfma_f32_32x32x16_bf16 v[50:65], v[192:195], v[82:85], v[50:65]
	ds_read_b128 v[192:195], v246 offset:16384
	v_pk_add_f32 v[90:91], v[90:91], v[142:143] op_sel_hi:[1,0]
	v_pk_add_f32 v[92:93], v[92:93], v[142:143] op_sel_hi:[1,0]
	v_pk_add_f32 v[94:95], v[94:95], v[142:143] op_sel_hi:[1,0]
	v_pk_add_f32 v[96:97], v[96:97], v[142:143] op_sel_hi:[1,0]
	v_exp_f32_e32 v90, v90
	v_mfma_f32_32x32x16_bf16 v[34:49], v[202:205], v[82:85], v[34:49]
	ds_read_b128 v[202:205], v246 offset:20480
	v_exp_f32_e32 v91, v91
	v_exp_f32_e32 v92, v92
	v_exp_f32_e32 v93, v93
	v_exp_f32_e32 v94, v94
	v_exp_f32_e32 v95, v95
	v_mfma_f32_32x32x16_bf16 v[18:33], v[210:213], v[82:85], v[18:33]
	ds_read_b128 v[210:213], v246 offset:24576
	v_exp_f32_e32 v96, v96
	v_exp_f32_e32 v97, v97
	v_pk_add_f32 v[252:253], v[252:253], v[90:91]
	v_pk_add_f32 v[252:253], v[252:253], v[92:93]
	v_cvt_pk_bf16_f32 v90, v90, v91
	v_mfma_f32_32x32x16_bf16 v[2:17], v[218:221], v[82:85], v[2:17]
	ds_read_b128 v[218:221], v246 offset:28672
	v_cvt_pk_bf16_f32 v91, v92, v93
	v_cvt_pk_bf16_f32 v92, v94, v95
	v_cvt_pk_bf16_f32 v93, v96, v97
	v_pk_add_f32 v[252:253], v[252:253], v[94:95]
	v_pk_add_f32 v[252:253], v[252:253], v[96:97]
	s_waitcnt lgkmcnt(4)
	v_mfma_f32_32x32x16_bf16 v[50:65], v[196:199], v[90:93], v[50:65]
	ds_read_b128 v[196:199], v247 offset:16384
	v_pk_add_f32 v[66:67], v[66:67], v[248:249] op_sel_hi:[1,0]
	v_pk_add_f32 v[68:69], v[68:69], v[248:249] op_sel_hi:[1,0]
	v_pk_add_f32 v[70:71], v[70:71], v[248:249] op_sel_hi:[1,0]
	v_pk_add_f32 v[72:73], v[72:73], v[248:249] op_sel_hi:[1,0]
	v_exp_f32_e32 v66, v66
	v_mfma_f32_32x32x16_bf16 v[34:49], v[206:209], v[90:93], v[34:49]
	ds_read_b128 v[206:209], v247 offset:20480
	v_exp_f32_e32 v67, v67
	v_exp_f32_e32 v68, v68
	v_exp_f32_e32 v69, v69
	v_exp_f32_e32 v70, v70
	v_exp_f32_e32 v71, v71
	v_mfma_f32_32x32x16_bf16 v[18:33], v[214:217], v[90:93], v[18:33]
	ds_read_b128 v[214:217], v247 offset:24576
	v_exp_f32_e32 v72, v72
	v_exp_f32_e32 v73, v73
	v_pk_add_f32 v[252:253], v[252:253], v[66:67]
	v_pk_add_f32 v[252:253], v[252:253], v[68:69]
	v_cvt_pk_bf16_f32 v66, v66, v67
	v_mfma_f32_32x32x16_bf16 v[2:17], v[222:225], v[90:93], v[2:17]
	ds_read_b128 v[222:225], v247 offset:28672
	v_cvt_pk_bf16_f32 v67, v68, v69
	v_cvt_pk_bf16_f32 v68, v70, v71
	v_cvt_pk_bf16_f32 v69, v72, v73
	v_pk_add_f32 v[252:253], v[252:253], v[70:71]
	v_pk_add_f32 v[252:253], v[252:253], v[72:73]
	s_waitcnt lgkmcnt(4)
	v_mfma_f32_32x32x16_bf16 v[50:65], v[192:195], v[66:69], v[50:65]
	v_pk_add_f32 v[74:75], v[74:75], v[248:249] op_sel_hi:[1,0]
	v_pk_add_f32 v[76:77], v[76:77], v[248:249] op_sel_hi:[1,0]
	v_pk_add_f32 v[78:79], v[78:79], v[248:249] op_sel_hi:[1,0]
	v_pk_add_f32 v[80:81], v[80:81], v[248:249] op_sel_hi:[1,0]
	v_exp_f32_e32 v74, v74
	v_mfma_f32_32x32x16_bf16 v[34:49], v[202:205], v[66:69], v[34:49]
	v_exp_f32_e32 v75, v75
	v_exp_f32_e32 v76, v76
	v_exp_f32_e32 v77, v77
	v_exp_f32_e32 v78, v78
	v_exp_f32_e32 v79, v79
	v_mfma_f32_32x32x16_bf16 v[18:33], v[210:213], v[66:69], v[18:33]
	v_exp_f32_e32 v80, v80
	v_exp_f32_e32 v81, v81
	v_pk_add_f32 v[252:253], v[252:253], v[74:75]
	v_pk_add_f32 v[252:253], v[252:253], v[76:77]
	v_cvt_pk_bf16_f32 v74, v74, v75
	v_mfma_f32_32x32x16_bf16 v[2:17], v[218:221], v[66:69], v[2:17]
	v_cvt_pk_bf16_f32 v75, v76, v77
	v_cvt_pk_bf16_f32 v76, v78, v79
	v_cvt_pk_bf16_f32 v77, v80, v81
	v_pk_add_f32 v[252:253], v[252:253], v[78:79]
	v_pk_add_f32 v[252:253], v[252:253], v[80:81]
	s_waitcnt lgkmcnt(0)
	v_mfma_f32_32x32x16_bf16 v[50:65], v[196:199], v[74:77], v[50:65]
	v_add_f32_e32 v250, v252, v253
	v_mfma_f32_32x32x16_bf16 v[34:49], v[206:209], v[74:77], v[34:49]
	v_add_f32_e32 v191, v191, v250
	v_mfma_f32_32x32x16_bf16 v[18:33], v[214:217], v[74:77], v[18:33]
	v_mfma_f32_32x32x16_bf16 v[2:17], v[222:225], v[74:77], v[2:17]
.La_endA0:
	ds_read_b128 v[192:195], v201 offset:32768
	ds_read_b128 v[202:205], v135 offset:32768
	ds_read_b128 v[210:213], v249 offset:32768
	ds_read_b128 v[218:221], v254 offset:32768
	ds_read_b128 v[196:199], v201 offset:40960
	ds_read_b128 v[206:209], v135 offset:40960
	ds_read_b128 v[214:217], v249 offset:40960
	ds_read_b128 v[222:225], v254 offset:40960
	s_add_i32 s5, s81, 3
	s_cmp_ge_u32 s5, s73
	s_cbranch_scc1 .La_qk_nodmaB0
	s_add_i32 s5, s82, 0x18000
	s_and_b32 s5, s5, 0x18000
	s_add_i32 s5, s72, s5
	s_mov_b32 m0, s5
	s_waitcnt lgkmcnt(4)
	v_mfma_f32_32x32x16_bf16 v[82:97], v[192:195], v[98:101], v[226:241]
	global_load_lds_dwordx4 v[140:141], off
	s_add_i32 m0, s5, 0x400
	v_add_f32_e32 v250, 0xc2800000, v137
	v_add_f32_e32 v143, v133, v121
	v_mfma_f32_32x32x16_bf16 v[82:97], v[202:205], v[102:105], v[82:97]
	global_load_lds_dwordx4 v[138:139], off
	s_add_i32 m0, s5, 0x4000
	v_fma_f32 v251, v127, v250, v188
	v_fma_f32 v142, v127, v250, -v132
	v_mfma_f32_32x32x16_bf16 v[82:97], v[210:213], v[106:109], v[82:97]
	global_load_lds_dwordx4 v134, s[44:45]
	s_add_i32 m0, s5, 0x4400
	v_max_f32_e32 v143, 0xff7fffff, v143
	v_add_f32_e32 v248, v142, v188
	v_mfma_f32_32x32x16_bf16 v[82:97], v[218:221], v[110:113], v[82:97]
	global_load_lds_dwordx4 v136, s[44:45]
	ds_read_b128 v[192:195], v244 offset:49152
	ds_read_b128 v[202:205], v244 offset:53248
	ds_read_b128 v[210:213], v244 offset:57344
	ds_read_b128 v[218:221], v244 offset:61440
	s_waitcnt lgkmcnt(4)
	v_mfma_f32_32x32x16_bf16 v[66:81], v[196:199], v[98:101], v[226:241]
	s_add_u32 s44, s44, 0xffffff80
	s_addc_u32 s45, s45, -1
	v_lshl_add_u64 v[138:139], v[138:139], 0, s[38:39]
	v_lshl_add_u64 v[140:141], v[140:141], 0, s[38:39]
	v_mfma_f32_32x32x16_bf16 v[66:81], v[206:209], v[102:105], v[66:81]
	v_max3_f32 v0, v82, v83, v84
	v_max3_f32 v0, v0, v85, v86
	v_mfma_f32_32x32x16_bf16 v[66:81], v[214:217], v[106:109], v[66:81]
	v_max3_f32 v0, v0, v87, v88
	v_max3_f32 v0, v0, v89, v90
	v_max3_f32 v0, v0, v91, v92
	v_mfma_f32_32x32x16_bf16 v[66:81], v[222:225], v[110:113], v[66:81]
	v_max3_f32 v0, v0, v93, v94
	v_max3_f32 v0, v0, v95, v96
	v_max_f32_e32 v0, v0, v97
; __device__ __forceinline__ int crow(int r, int hi) { return (r & 3) + 8 * (r >> 2) + 4 * hi; }
; __device__ __forceinline__ float ex2(float v) { return __builtin_amdgcn_exp2f(v); }
; __device__ __forceinline__ void unit(LAS unsigned char* lds, bf16_t* P1, const bf16_t* vaT, int b, int h, int qblk, float lam, const float* subln_w, const float* khalf) {
;     ...
;         const int kv0 = 64 * j;
;         if (j >= NT - 2) {
; #pragma unroll
;             for (int r = 0; r < 16; ++r) { const int kv = kv0 + crow(r, hi); if (kv > qrow) S0[r] = -INFINITY; if (kv + 32 > qrow) S1[r] = -INFINITY; }
;         }
;         const float tb0 = sl2 * (float)(kv0 - qrow), tb1 = tb0 + sl2 * 32.f;
;         float mx0 = S0[0], mx1 = S1[0];
; #pragma unroll
;         for (int r = 1; r < 16; ++r) { mx0 = fmaxf(mx0, S0[r]); mx1 = fmaxf(mx1, S1[r]); }
;         float mt = fmaxf(mx0 + tb0, mx1 + tb1); mt = fmaxf(mt, __shfl_xor(mt, 32));
;         const bool skip = __all((mt < m - 24.f) || (mt == -INFINITY));
;         if (!skip) {
;         const float mn = fmaxf(m, mt); const float alpha = ex2(m - mn); m = mn;
.La_qk_doneB0:
	ds_read_b128 v[196:199], v245 offset:49152
	ds_read_b128 v[206:209], v245 offset:53248
	ds_read_b128 v[214:217], v245 offset:57344
	ds_read_b128 v[222:225], v245 offset:61440
	s_nop 3
	v_add_u32_e32 v243, s100, v189
	v_add_u32_e32 v130, 0x60, v243
	v_add_u32_e32 v131, 64, v243
	v_cmp_le_i32_e32 vcc, v130, v125
	s_nop 6
	v_cndmask_b32_e32 v66, v184, v66, vcc
	v_cmp_lt_i32_e32 vcc, v131, v125
	s_nop 1
	v_cndmask_b32_e32 v83, v184, v83, vcc
	v_cmp_le_i32_e32 vcc, v131, v125
	v_add_u32_e32 v131, 0x61, v243
	s_nop 0
	v_cndmask_b32_e32 v82, v184, v82, vcc
	v_cmp_le_i32_e32 vcc, v131, v125
	v_add_u32_e32 v131, 0x42, v243
	s_nop 0
	v_cndmask_b32_e32 v67, v184, v67, vcc
	v_cmp_le_i32_e32 vcc, v131, v125
	v_add_u32_e32 v131, 0x62, v243
	s_nop 0
	v_cndmask_b32_e32 v84, v184, v84, vcc
	v_cmp_le_i32_e32 vcc, v131, v125
	v_add_u32_e32 v131, 0x43, v243
	s_nop 0
	v_cndmask_b32_e32 v68, v184, v68, vcc
	v_cmp_le_i32_e32 vcc, v131, v125
	v_add_u32_e32 v131, 0x63, v243
	s_nop 0
	v_cndmask_b32_e32 v85, v184, v85, vcc
	v_cmp_le_i32_e32 vcc, v131, v125
	v_add_u32_e32 v131, 0x48, v243
	s_nop 0
	v_cndmask_b32_e32 v69, v184, v69, vcc
	v_cmp_le_i32_e32 vcc, v131, v125
	v_add_u32_e32 v131, 0x68, v243
	s_nop 0
	v_cndmask_b32_e32 v86, v184, v86, vcc
	v_cmp_le_i32_e32 vcc, v131, v125
	v_add_u32_e32 v131, 0x49, v243
	s_nop 0
	v_cndmask_b32_e32 v70, v184, v70, vcc
	v_cmp_le_i32_e32 vcc, v131, v125
	v_add_u32_e32 v131, 0x69, v243
	s_nop 0
	v_cndmask_b32_e32 v87, v184, v87, vcc
	v_cmp_le_i32_e32 vcc, v131, v125
	v_add_u32_e32 v131, 0x4a, v243
	s_nop 0
	v_cndmask_b32_e32 v71, v184, v71, vcc
	v_cmp_le_i32_e32 vcc, v131, v125
	v_add_u32_e32 v131, 0x6a, v243
	s_nop 0
	v_cndmask_b32_e32 v88, v184, v88, vcc
	v_cmp_le_i32_e32 vcc, v131, v125
	v_add_u32_e32 v131, 0x4b, v243
	s_nop 0
	v_cndmask_b32_e32 v72, v184, v72, vcc
	v_cmp_le_i32_e32 vcc, v131, v125
	v_add_u32_e32 v131, 0x6b, v243
	s_nop 0
	v_cndmask_b32_e32 v89, v184, v89, vcc
	v_cmp_le_i32_e32 vcc, v131, v125
	v_add_u32_e32 v131, 0x50, v243
	s_nop 0
	v_cndmask_b32_e32 v73, v184, v73, vcc
	v_cmp_le_i32_e32 vcc, v131, v125
	v_add_u32_e32 v131, 0x70, v243
	s_nop 0
	v_cndmask_b32_e32 v90, v184, v90, vcc
	v_cmp_le_i32_e32 vcc, v131, v125
	v_add_u32_e32 v131, 0x51, v243
	s_nop 0
	v_cndmask_b32_e32 v74, v184, v74, vcc
	v_cmp_le_i32_e32 vcc, v131, v125
	v_add_u32_e32 v131, 0x71, v243
	s_nop 0
	v_cndmask_b32_e32 v91, v184, v91, vcc
	v_cmp_le_i32_e32 vcc, v131, v125
	v_add_u32_e32 v131, 0x52, v243
	s_nop 0
	v_cndmask_b32_e32 v75, v184, v75, vcc
	v_cmp_le_i32_e32 vcc, v131, v125
	v_add_u32_e32 v131, 0x72, v243
	s_nop 0
	v_cndmask_b32_e32 v92, v184, v92, vcc
	v_cmp_le_i32_e32 vcc, v131, v125
	v_add_u32_e32 v131, 0x53, v243
	s_nop 0
	v_cndmask_b32_e32 v76, v184, v76, vcc
	v_cmp_le_i32_e32 vcc, v131, v125
	v_add_u32_e32 v131, 0x73, v243
	s_nop 0
	v_cndmask_b32_e32 v93, v184, v93, vcc
	v_cmp_le_i32_e32 vcc, v131, v125
	v_add_u32_e32 v131, 0x58, v243
	s_nop 0
	v_cndmask_b32_e32 v77, v184, v77, vcc
	v_cmp_le_i32_e32 vcc, v131, v125
	v_add_u32_e32 v131, 0x78, v243
	s_nop 0
	v_cndmask_b32_e32 v94, v184, v94, vcc
	v_cmp_le_i32_e32 vcc, v131, v125
	v_add_u32_e32 v131, 0x59, v243
	s_nop 0
	v_cndmask_b32_e32 v78, v184, v78, vcc
	v_cmp_le_i32_e32 vcc, v131, v125
	v_add_u32_e32 v131, 0x79, v243
	s_nop 0
	v_cndmask_b32_e32 v95, v184, v95, vcc
	v_cmp_le_i32_e32 vcc, v131, v125
	v_add_u32_e32 v131, 0x5a, v243
	s_nop 0
	v_cndmask_b32_e32 v79, v184, v79, vcc
	v_cmp_le_i32_e32 vcc, v131, v125
	v_add_u32_e32 v131, 0x7a, v243
	s_nop 0
	v_cndmask_b32_e32 v96, v184, v96, vcc
	v_cmp_le_i32_e32 vcc, v131, v125
	v_add_u32_e32 v131, 0x5b, v243
	v_add_u32_e32 v243, 0x7b, v243
	v_cndmask_b32_e32 v80, v184, v80, vcc
	v_cmp_le_i32_e32 vcc, v131, v125
	s_nop 1
	v_cndmask_b32_e32 v97, v184, v97, vcc
	v_cmp_le_i32_e32 vcc, v243, v125
	s_nop 1
	v_cndmask_b32_e32 v81, v184, v81, vcc
	v_max3_f32 v0, v82, v83, v84
	v_max3_f32 v0, v0, v85, v86
	v_max3_f32 v0, v0, v87, v88
	v_max3_f32 v0, v0, v89, v90
	v_max3_f32 v0, v0, v91, v92
	v_max3_f32 v0, v0, v93, v94
	v_max3_f32 v0, v0, v95, v96
	v_max_f32_e32 v0, v0, v97
	v_fmac_f32_e32 v0, v127, v250
	s_nop 1
	v_max3_f32 v120, v66, v67, v68
	v_max3_f32 v120, v120, v69, v70
	v_max3_f32 v120, v120, v71, v72
	v_max3_f32 v120, v120, v73, v74
	v_max3_f32 v120, v120, v75, v76
	v_max3_f32 v120, v120, v77, v78
	v_max3_f32 v120, v120, v79, v80
	v_max_f32_e32 v120, v120, v81
	v_add_f32_e32 v120, v251, v120
	v_max_f32_e32 v0, v0, v120
	v_mov_b32_e32 v120, v0
	s_nop 1
	v_permlane32_swap_b32_e32 v0, v120
	v_max_f32_e32 v0, v0, v120
	v_cmp_lt_f32_e32 vcc, v0, v143
	v_max_f32_e32 v133, v133, v0
	v_mov_b32_e32 v255, v0
	s_andn2_b64 s[2:3], exec, vcc
	s_cbranch_scc0 .La_endB0
; #define LAS __attribute__((address_space(3)))
; __device__ __forceinline__ unsigned cvtpk(float lo, float hi) { return pg8::cvt_pk_bf16(lo, hi); }
; __device__ __forceinline__ float ex2(float v) { return __builtin_amdgcn_exp2f(v); }
; #define MFMA32(a, b, c) __builtin_amdgcn_mfma_f32_32x32x16_bf16((a), (b), (c), 0, 0, 0)
; __device__ __forceinline__ void unit(LAS unsigned char* lds, bf16_t* P1, const bf16_t* vaT, int b, int h, int qblk, float lam, const float* subln_w, const float* khalf) {
;     ...
;         const float mn = fmaxf(m, mt); const float alpha = ex2(m - mn); m = mn;
;         const float c0 = tb0 - mn, c1 = tb1 - mn;
;         f32x2 ps2 = (f32x2){0.f, 0.f};
; #pragma unroll
;         for (int r = 0; r < 16; r += 2) { f32x2 a = (f32x2){S0[r], S0[r + 1]} + c0, bq = (f32x2){S1[r], S1[r + 1]} + c1;
;             a.x = ex2(a.x); a.y = ex2(a.y); bq.x = ex2(bq.x); bq.y = ex2(bq.y); S0[r] = a.x; S0[r + 1] = a.y; S1[r] = bq.x; S1[r + 1] = bq.y; ps2 = ps2 + a; ps2 = ps2 + bq; }
;         l = l * alpha + (ps2.x + ps2.y);
;         if (__any(alpha != 1.f)) {
; #pragma unroll
;             for (int d = 0; d < 4; ++d) O[d] = O[d] * alpha;
;         }
;         u32x4 pk[2][2];
; #pragma unroll
;         for (int s = 0; s < 2; ++s) {
;             pk[0][s] = (u32x4){cvtpk(S0[8 * s + 0], S0[8 * s + 1]), cvtpk(S0[8 * s + 2], S0[8 * s + 3]), cvtpk(S0[8 * s + 4], S0[8 * s + 5]), cvtpk(S0[8 * s + 6], S0[8 * s + 7])};
;             pk[1][s] = (u32x4){cvtpk(S1[8 * s + 0], S1[8 * s + 1]), cvtpk(S1[8 * s + 2], S1[8 * s + 3]), cvtpk(S1[8 * s + 4], S1[8 * s + 5]), cvtpk(S1[8 * s + 6], S1[8 * s + 7])};
;         }
; #pragma unroll
;         for (int d = 0; d < 4; ++d)
; #pragma unroll
;             for (int t2 = 0; t2 < 2; ++t2)
; #pragma unroll
;                 for (int s = 0; s < 2; ++s) {
;                     const bf16x8 vf = *(const LAS bf16x8*)(kb + voff[2 * t2 + s] + d * 32 * 128);
;                     O[d] = MFMA32(vf, __builtin_bit_cast(bf16x8, pk[t2][s]), O[d]);
;                 }
;         }
	v_pk_add_f32 v[82:83], v[82:83], v[142:143] op_sel_hi:[1,0]
	v_pk_add_f32 v[84:85], v[84:85], v[142:143] op_sel_hi:[1,0]
	v_pk_add_f32 v[86:87], v[86:87], v[142:143] op_sel_hi:[1,0]
	v_pk_add_f32 v[88:89], v[88:89], v[142:143] op_sel_hi:[1,0]
	v_exp_f32_e32 v82, v82
	v_exp_f32_e32 v83, v83
	v_exp_f32_e32 v84, v84
	v_exp_f32_e32 v85, v85
	v_exp_f32_e32 v86, v86
	v_exp_f32_e32 v87, v87
	v_exp_f32_e32 v88, v88
	v_exp_f32_e32 v89, v89
	v_pk_add_f32 v[252:253], v[82:83], v[84:85]
	v_cvt_pk_bf16_f32 v82, v82, v83
	v_cvt_pk_bf16_f32 v83, v84, v85
	v_cvt_pk_bf16_f32 v84, v86, v87
	v_cvt_pk_bf16_f32 v85, v88, v89
	v_pk_add_f32 v[252:253], v[252:253], v[86:87]
	v_pk_add_f32 v[252:253], v[252:253], v[88:89]
	s_waitcnt lgkmcnt(4)
	v_mfma_f32_32x32x16_bf16 v[50:65], v[192:195], v[82:85], v[50:65]
	ds_read_b128 v[192:195], v246 offset:49152
	v_pk_add_f32 v[90:91], v[90:91], v[142:143] op_sel_hi:[1,0]
	v_pk_add_f32 v[92:93], v[92:93], v[142:143] op_sel_hi:[1,0]
	v_pk_add_f32 v[94:95], v[94:95], v[142:143] op_sel_hi:[1,0]
	v_pk_add_f32 v[96:97], v[96:97], v[142:143] op_sel_hi:[1,0]
	v_exp_f32_e32 v90, v90
	v_mfma_f32_32x32x16_bf16 v[34:49], v[202:205], v[82:85], v[34:49]
	ds_read_b128 v[202:205], v246 offset:53248
	v_exp_f32_e32 v91, v91
	v_exp_f32_e32 v92, v92
	v_exp_f32_e32 v93, v93
	v_exp_f32_e32 v94, v94
	v_exp_f32_e32 v95, v95
	v_mfma_f32_32x32x16_bf16 v[18:33], v[210:213], v[82:85], v[18:33]
	ds_read_b128 v[210:213], v246 offset:57344
	v_exp_f32_e32 v96, v96
	v_exp_f32_e32 v97, v97
	v_pk_add_f32 v[252:253], v[252:253], v[90:91]
	v_pk_add_f32 v[252:253], v[252:253], v[92:93]
	v_cvt_pk_bf16_f32 v90, v90, v91
	v_mfma_f32_32x32x16_bf16 v[2:17], v[218:221], v[82:85], v[2:17]
	ds_read_b128 v[218:221], v246 offset:61440
	v_cvt_pk_bf16_f32 v91, v92, v93
	v_cvt_pk_bf16_f32 v92, v94, v95
	v_cvt_pk_bf16_f32 v93, v96, v97
	v_pk_add_f32 v[252:253], v[252:253], v[94:95]
	v_pk_add_f32 v[252:253], v[252:253], v[96:97]
	s_waitcnt lgkmcnt(4)
	v_mfma_f32_32x32x16_bf16 v[50:65], v[196:199], v[90:93], v[50:65]
	ds_read_b128 v[196:199], v247 offset:49152
	v_pk_add_f32 v[66:67], v[66:67], v[248:249] op_sel_hi:[1,0]
	v_pk_add_f32 v[68:69], v[68:69], v[248:249] op_sel_hi:[1,0]
	v_pk_add_f32 v[70:71], v[70:71], v[248:249] op_sel_hi:[1,0]
	v_pk_add_f32 v[72:73], v[72:73], v[248:249] op_sel_hi:[1,0]
	v_exp_f32_e32 v66, v66
	v_mfma_f32_32x32x16_bf16 v[34:49], v[206:209], v[90:93], v[34:49]
	ds_read_b128 v[206:209], v247 offset:53248
	v_exp_f32_e32 v67, v67
	v_exp_f32_e32 v68, v68
	v_exp_f32_e32 v69, v69
	v_exp_f32_e32 v70, v70
	v_exp_f32_e32 v71, v71
	v_mfma_f32_32x32x16_bf16 v[18:33], v[214:217], v[90:93], v[18:33]
	ds_read_b128 v[214:217], v247 offset:57344
	v_exp_f32_e32 v72, v72
	v_exp_f32_e32 v73, v73
	v_pk_add_f32 v[252:253], v[252:253], v[66:67]
	v_pk_add_f32 v[252:253], v[252:253], v[68:69]
	v_cvt_pk_bf16_f32 v66, v66, v67
	v_mfma_f32_32x32x16_bf16 v[2:17], v[222:225], v[90:93], v[2:17]
	ds_read_b128 v[222:225], v247 offset:61440
	v_cvt_pk_bf16_f32 v67, v68, v69
	v_cvt_pk_bf16_f32 v68, v70, v71
	v_cvt_pk_bf16_f32 v69, v72, v73
	v_pk_add_f32 v[252:253], v[252:253], v[70:71]
	v_pk_add_f32 v[252:253], v[252:253], v[72:73]
	s_waitcnt lgkmcnt(4)
	v_mfma_f32_32x32x16_bf16 v[50:65], v[192:195], v[66:69], v[50:65]
	v_pk_add_f32 v[74:75], v[74:75], v[248:249] op_sel_hi:[1,0]
	v_pk_add_f32 v[76:77], v[76:77], v[248:249] op_sel_hi:[1,0]
	v_pk_add_f32 v[78:79], v[78:79], v[248:249] op_sel_hi:[1,0]
	v_pk_add_f32 v[80:81], v[80:81], v[248:249] op_sel_hi:[1,0]
	v_exp_f32_e32 v74, v74
	v_mfma_f32_32x32x16_bf16 v[34:49], v[202:205], v[66:69], v[34:49]
	v_exp_f32_e32 v75, v75
	v_exp_f32_e32 v76, v76
	v_exp_f32_e32 v77, v77
	v_exp_f32_e32 v78, v78
	v_exp_f32_e32 v79, v79
	v_mfma_f32_32x32x16_bf16 v[18:33], v[210:213], v[66:69], v[18:33]
	v_exp_f32_e32 v80, v80
	v_exp_f32_e32 v81, v81
	v_pk_add_f32 v[252:253], v[252:253], v[74:75]
	v_pk_add_f32 v[252:253], v[252:253], v[76:77]
	v_cvt_pk_bf16_f32 v74, v74, v75
	v_mfma_f32_32x32x16_bf16 v[2:17], v[218:221], v[66:69], v[2:17]
	v_cvt_pk_bf16_f32 v75, v76, v77
	v_cvt_pk_bf16_f32 v76, v78, v79
	v_cvt_pk_bf16_f32 v77, v80, v81
	v_pk_add_f32 v[252:253], v[252:253], v[78:79]
	v_pk_add_f32 v[252:253], v[252:253], v[80:81]
	s_waitcnt lgkmcnt(0)
	v_mfma_f32_32x32x16_bf16 v[50:65], v[196:199], v[74:77], v[50:65]
	v_add_f32_e32 v250, v252, v253
	v_mfma_f32_32x32x16_bf16 v[34:49], v[206:209], v[74:77], v[34:49]
	v_add_f32_e32 v191, v191, v250
	v_mfma_f32_32x32x16_bf16 v[18:33], v[214:217], v[74:77], v[18:33]
	v_mfma_f32_32x32x16_bf16 v[2:17], v[222:225], v[74:77], v[2:17]
.La_endB0:
	s_add_i32 s80, s80, 2
	s_and_b32 s80, s80, 3
	s_add_i32 s4, s59, s76
	s_add_i32 s81, s81, 2
	s_sub_i32 s76, s76, 0x80
	v_add_f32_e32 v137, 0xc3000000, v137
	s_cmp_eq_u32 s4, 0
	s_cbranch_scc1 .LBB0_420

; #define LAS __attribute__((address_space(3)))
; __device__ __forceinline__ void unit(LAS unsigned char* lds, bf16_t* P1, const bf16_t* vaT, int b, int h, int qblk, float lam, const float* subln_w, const float* khalf) {
;     ...
;         if (jj + 2 < NT) asm volatile("s_waitcnt vmcnt(8) lgkmcnt(0)\n\ts_barrier" ::: "memory"); else if (jj + 1 < NT) asm volatile("s_waitcnt vmcnt(4) lgkmcnt(0)\n\ts_barrier" ::: "memory"); else asm volatile("s_waitcnt vmcnt(0) lgkmcnt(0)\n\ts_barrier" ::: "memory");
;         { typedef int i32x4 __attribute__((ext_vector_type(4)));
;           const i32x4 fa = *(const LAS i32x4*)(lds + 4 * STG + (jj & 1) * 32), fb = *(const LAS i32x4*)(lds + 4 * STG + (jj & 1) * 32 + 16);
;           if (((fa[0] + fa[1]) + (fa[2] + fa[3])) + ((fb[0] + fb[1]) + (fb[2] + fb[3])) == 8) break; }
;         if (jj + 3 < NT) { DMA_TILE(j - 3, (stg + 3) & 3); }
;         const LAS unsigned char* kb = lds + stg * STG;
;         stg = (stg + 1) & 3;
;         f32x16 S0, S1;
;         { float slv = sl2; asm volatile("" : "+v"(slv));
; #pragma unroll
;           for (int r = 0; r < 16; ++r) { S0[r] = __builtin_fmaf(slv, (float)((r & 3) + 8 * (r >> 2)), sl2h); S1[r] = S0[r]; } }
; #pragma unroll
;         for (int ks = 0; ks < 4; ++ks) {
;             const bf16x8 a0 = *(const LAS bf16x8*)(kb + koff[ks]);
;             const bf16x8 a1 = *(const LAS bf16x8*)(kb + koff[ks] + 32 * 256);
;             S0 = MFMA32(a0, qf[ks], S0); S1 = MFMA32(a1, qf[ks], S1);
;         }
;         const int kv0 = 64 * j;
;         if (j >= NT - 2) {
; #pragma unroll
;             for (int r = 0; r < 16; ++r) { const int kv = kv0 + crow(r, hi); if (kv > qrow) S0[r] = -INFINITY; if (kv + 32 > qrow) S1[r] = -INFINITY; }
;         }
;         const float tb0 = sl2 * (float)(kv0 - qrow), tb1 = tb0 + sl2 * 32.f;
;         float mx0 = S0[0], mx1 = S1[0];
; #pragma unroll
;         for (int r = 1; r < 16; ++r) { mx0 = fmaxf(mx0, S0[r]); mx1 = fmaxf(mx1, S1[r]); }
;         float mt = fmaxf(mx0 + tb0, mx1 + tb1); mt = fmaxf(mt, __shfl_xor(mt, 32));
;         const bool skip = __all((mt < m - 24.f) || (mt == -INFINITY));
;         if (!skip) {
;         const float mn = fmaxf(m, mt); const float alpha = ex2(m - mn); m = mn;
;         const float c0 = tb0 - mn, c1 = tb1 - mn;
;         f32x2 ps2 = (f32x2){0.f, 0.f};
; #pragma unroll
.La_flag_done:
	s_or_b64 exec, exec, s[4:5]
	s_waitcnt vmcnt(0) lgkmcnt(0)
	s_barrier
.La_after_bar:
	s_lshl_b32 s82, s80, 15
	s_add_i32 s83, s82, 0x8000
	s_sub_i32 s100, s76, 64
	s_and_b32 s2, s81, 2
	s_lshl_b32 s2, s2, 4
	s_add_i32 s2, s2, 0x20000
	v_mov_b32_e32 v70, s2
	ds_read_b128 v[66:69], v70
	ds_read_b128 v[70:73], v70 offset:16
	v_add3_u32 v201, s82, v129, v151
	v_add3_u32 v135, s82, v185, v151
	v_add3_u32 v249, s82, v186, v151
	v_add3_u32 v254, s82, v187, v151
	ds_read_b128 v[192:195], v201
	ds_read_b128 v[202:205], v135
	ds_read_b128 v[210:213], v249
	ds_read_b128 v[218:221], v254
	ds_read_b128 v[196:199], v201 offset:8192
	ds_read_b128 v[206:209], v135 offset:8192
	ds_read_b128 v[214:217], v249 offset:8192
	ds_read_b128 v[222:225], v254 offset:8192
	s_waitcnt lgkmcnt(8)
	v_add3_u32 v66, v66, v67, v68
	v_add3_u32 v69, v69, v70, v71
	v_add_u32_e32 v72, v72, v73
	v_add3_u32 v66, v66, v69, v72
	v_cmp_eq_u32_e32 vcc, 8, v66
	s_cbranch_vccnz .LBB0_420
	s_add_i32 s5, s81, 2
	s_cmp_ge_u32 s5, s73
	s_cbranch_scc1 .La_qk_nodmaA
	s_add_i32 s5, s82, 0x10000
	s_and_b32 s5, s5, 0x18000
	s_add_i32 s5, s72, s5
	s_mov_b32 m0, s5
	s_waitcnt lgkmcnt(4)
	v_mfma_f32_32x32x16_bf16 v[82:97], v[192:195], v[98:101], v[226:241]
	global_load_lds_dwordx4 v[140:141], off
	s_add_i32 m0, s5, 0x400
	v_add_u32_e32 v244, s82, v168
	v_add_u32_e32 v245, s82, v169
	v_add_u32_e32 v246, s82, v170
	v_mfma_f32_32x32x16_bf16 v[82:97], v[202:205], v[102:105], v[82:97]
	global_load_lds_dwordx4 v[138:139], off
	s_add_i32 m0, s5, 0x4000
	v_add_u32_e32 v247, s82, v171
	v_add_f32_e32 v143, v133, v121
	v_fma_f32 v251, v127, v137, v188
	v_mfma_f32_32x32x16_bf16 v[82:97], v[210:213], v[106:109], v[82:97]
	global_load_lds_dwordx4 v134, s[44:45]
	s_add_i32 m0, s5, 0x4400
	v_fma_f32 v142, v127, v137, -v132
	v_max_f32_e32 v143, 0xff7fffff, v143
	v_add_f32_e32 v248, v142, v188
	v_mfma_f32_32x32x16_bf16 v[82:97], v[218:221], v[110:113], v[82:97]
	global_load_lds_dwordx4 v136, s[44:45]
	v_fma_f32 v255, v188, -2.0, v255
	v_add_f32_e32 v243, 4.0, v143
	ds_read_b128 v[192:195], v244 offset:16384
	ds_read_b128 v[202:205], v244 offset:20480
	ds_read_b128 v[210:213], v244 offset:24576
	ds_read_b128 v[218:221], v244 offset:28672
	s_waitcnt lgkmcnt(4)
	v_mfma_f32_32x32x16_bf16 v[66:81], v[196:199], v[98:101], v[226:241]
	s_add_u32 s44, s44, 0xffffff80
	s_addc_u32 s45, s45, -1
	v_lshl_add_u64 v[138:139], v[138:139], 0, s[38:39]
	v_lshl_add_u64 v[140:141], v[140:141], 0, s[38:39]
	v_mfma_f32_32x32x16_bf16 v[66:81], v[206:209], v[102:105], v[66:81]
	v_max3_f32 v0, v82, v83, v84
	v_max3_f32 v0, v0, v85, v86
	v_max3_f32 v0, v0, v87, v88
	v_max3_f32 v0, v0, v89, v90
	v_pk_add_f32 v[82:83], v[82:83], v[142:143] op_sel_hi:[1,0]
	v_pk_add_f32 v[84:85], v[84:85], v[142:143] op_sel_hi:[1,0]
	v_mfma_f32_32x32x16_bf16 v[66:81], v[214:217], v[106:109], v[66:81]
	v_pk_add_f32 v[86:87], v[86:87], v[142:143] op_sel_hi:[1,0]
	v_pk_add_f32 v[88:89], v[88:89], v[142:143] op_sel_hi:[1,0]
	v_exp_f32_e32 v82, v82
	v_exp_f32_e32 v83, v83
	v_exp_f32_e32 v84, v84
	v_max3_f32 v0, v0, v91, v92
	v_mfma_f32_32x32x16_bf16 v[66:81], v[222:225], v[110:113], v[66:81]
	v_exp_f32_e32 v85, v85
	v_exp_f32_e32 v86, v86
	v_exp_f32_e32 v87, v87
	v_max3_f32 v0, v0, v93, v94
	v_exp_f32_e32 v88, v88
	v_exp_f32_e32 v89, v89
	v_max3_f32 v0, v0, v95, v96
	v_max_f32_e32 v0, v0, v97
	v_cmp_ge_f32_e32 vcc, v255, v243
.La_qk_doneA:
	ds_read_b128 v[196:199], v245 offset:16384
	ds_read_b128 v[206:209], v245 offset:20480
	ds_read_b128 v[214:217], v245 offset:24576
	ds_read_b128 v[222:225], v245 offset:28672
	s_cbranch_vccz .La_maxA
.La_nomaxA:
	v_pk_add_f32 v[252:253], v[82:83], v[84:85]
	v_cvt_pk_bf16_f32 v82, v82, v83
	v_cvt_pk_bf16_f32 v83, v84, v85
	v_cvt_pk_bf16_f32 v84, v86, v87
	v_cvt_pk_bf16_f32 v85, v88, v89
	v_pk_add_f32 v[252:253], v[252:253], v[86:87]
	v_pk_add_f32 v[252:253], v[252:253], v[88:89]
	s_waitcnt lgkmcnt(4)
	v_mfma_f32_32x32x16_bf16 v[50:65], v[192:195], v[82:85], v[50:65]
	ds_read_b128 v[192:195], v246 offset:16384
	v_pk_add_f32 v[90:91], v[90:91], v[142:143] op_sel_hi:[1,0]
	v_pk_add_f32 v[92:93], v[92:93], v[142:143] op_sel_hi:[1,0]
	v_pk_add_f32 v[94:95], v[94:95], v[142:143] op_sel_hi:[1,0]
	v_pk_add_f32 v[96:97], v[96:97], v[142:143] op_sel_hi:[1,0]
	v_exp_f32_e32 v90, v90
	v_mfma_f32_32x32x16_bf16 v[34:49], v[202:205], v[82:85], v[34:49]
	ds_read_b128 v[202:205], v246 offset:20480
	v_exp_f32_e32 v91, v91
	v_exp_f32_e32 v92, v92
	v_exp_f32_e32 v93, v93
	v_exp_f32_e32 v94, v94
	v_exp_f32_e32 v95, v95
	v_mfma_f32_32x32x16_bf16 v[18:33], v[210:213], v[82:85], v[18:33]
	ds_read_b128 v[210:213], v246 offset:24576
	v_exp_f32_e32 v96, v96
	v_exp_f32_e32 v97, v97
	v_pk_add_f32 v[252:253], v[252:253], v[90:91]
	v_pk_add_f32 v[252:253], v[252:253], v[92:93]
	v_cvt_pk_bf16_f32 v90, v90, v91
	v_mfma_f32_32x32x16_bf16 v[2:17], v[218:221], v[82:85], v[2:17]
	ds_read_b128 v[218:221], v246 offset:28672
	v_cvt_pk_bf16_f32 v91, v92, v93
	v_cvt_pk_bf16_f32 v92, v94, v95
	v_cvt_pk_bf16_f32 v93, v96, v97
	v_pk_add_f32 v[252:253], v[252:253], v[94:95]
	v_pk_add_f32 v[252:253], v[252:253], v[96:97]
	s_waitcnt lgkmcnt(4)
; __device__ __forceinline__ void unit(LAS unsigned char* lds, bf16_t* P1, const bf16_t* vaT, int b, int h, int qblk, float lam, const float* subln_w, const float* khalf) {
;     ...
;         if (jj + 3 < NT) { DMA_TILE(j - 3, (stg + 3) & 3); }
;         const LAS unsigned char* kb = lds + stg * STG;
;         stg = (stg + 1) & 3;
;         f32x16 S0, S1;
;         { float slv = sl2; asm volatile("" : "+v"(slv));
; #pragma unroll
;           for (int r = 0; r < 16; ++r) { S0[r] = __builtin_fmaf(slv, (float)((r & 3) + 8 * (r >> 2)), sl2h); S1[r] = S0[r]; } }
; #pragma unroll
;         for (int ks = 0; ks < 4; ++ks) {
;             const bf16x8 a0 = *(const LAS bf16x8*)(kb + koff[ks]);
;             const bf16x8 a1 = *(const LAS bf16x8*)(kb + koff[ks] + 32 * 256);
;             S0 = MFMA32(a0, qf[ks], S0); S1 = MFMA32(a1, qf[ks], S1);
;         }
;     ...
;         const float mn = fmaxf(m, mt); const float alpha = ex2(m - mn); m = mn;
;         const float c0 = tb0 - mn, c1 = tb1 - mn;
;         f32x2 ps2 = (f32x2){0.f, 0.f};
; #pragma unroll
;         for (int r = 0; r < 16; r += 2) { f32x2 a = (f32x2){S0[r], S0[r + 1]} + c0, bq = (f32x2){S1[r], S1[r + 1]} + c1;
;             a.x = ex2(a.x); a.y = ex2(a.y); bq.x = ex2(bq.x); bq.y = ex2(bq.y); S0[r] = a.x; S0[r + 1] = a.y; S1[r] = bq.x; S1[r + 1] = bq.y; ps2 = ps2 + a; ps2 = ps2 + bq; }
;         l = l * alpha + (ps2.x + ps2.y);
;         if (__any(alpha != 1.f)) {
; #pragma unroll
;             for (int d = 0; d < 4; ++d) O[d] = O[d] * alpha;
;         }
;         u32x4 pk[2][2];
; #pragma unroll
;         for (int s = 0; s < 2; ++s) {
;             pk[0][s] = (u32x4){cvtpk(S0[8 * s + 0], S0[8 * s + 1]), cvtpk(S0[8 * s + 2], S0[8 * s + 3]), cvtpk(S0[8 * s + 4], S0[8 * s + 5]), cvtpk(S0[8 * s + 6], S0[8 * s + 7])};
;             pk[1][s] = (u32x4){cvtpk(S1[8 * s + 0], S1[8 * s + 1]), cvtpk(S1[8 * s + 2], S1[8 * s + 3]), cvtpk(S1[8 * s + 4], S1[8 * s + 5]), cvtpk(S1[8 * s + 6], S1[8 * s + 7])};
;         }
; #pragma unroll
;         for (int d = 0; d < 4; ++d)
; #pragma unroll
;             for (int t2 = 0; t2 < 2; ++t2)
; #pragma unroll
;                 for (int s = 0; s < 2; ++s) {
;                     const bf16x8 vf = *(const LAS bf16x8*)(kb + voff[2 * t2 + s] + d * 32 * 128);
;                     O[d] = MFMA32(vf, __builtin_bit_cast(bf16x8, pk[t2][s]), O[d]);
;                 }
;         }
	v_mfma_f32_32x32x16_bf16 v[50:65], v[196:199], v[90:93], v[50:65]
	ds_read_b128 v[196:199], v247 offset:16384
	v_pk_add_f32 v[66:67], v[66:67], v[248:249] op_sel_hi:[1,0]
	v_pk_add_f32 v[68:69], v[68:69], v[248:249] op_sel_hi:[1,0]
	v_pk_add_f32 v[70:71], v[70:71], v[248:249] op_sel_hi:[1,0]
	v_pk_add_f32 v[72:73], v[72:73], v[248:249] op_sel_hi:[1,0]
	v_exp_f32_e32 v66, v66
	v_mfma_f32_32x32x16_bf16 v[34:49], v[206:209], v[90:93], v[34:49]
	ds_read_b128 v[206:209], v247 offset:20480
	v_exp_f32_e32 v67, v67
	v_exp_f32_e32 v68, v68
	v_exp_f32_e32 v69, v69
	v_exp_f32_e32 v70, v70
	v_exp_f32_e32 v71, v71
	v_mfma_f32_32x32x16_bf16 v[18:33], v[214:217], v[90:93], v[18:33]
	ds_read_b128 v[214:217], v247 offset:24576
	v_exp_f32_e32 v72, v72
	v_exp_f32_e32 v73, v73
	v_pk_add_f32 v[252:253], v[252:253], v[66:67]
	v_pk_add_f32 v[252:253], v[252:253], v[68:69]
	v_cvt_pk_bf16_f32 v66, v66, v67
	v_mfma_f32_32x32x16_bf16 v[2:17], v[222:225], v[90:93], v[2:17]
	ds_read_b128 v[222:225], v247 offset:28672
	v_cvt_pk_bf16_f32 v67, v68, v69
	v_cvt_pk_bf16_f32 v68, v70, v71
	v_cvt_pk_bf16_f32 v69, v72, v73
	v_pk_add_f32 v[252:253], v[252:253], v[70:71]
	v_pk_add_f32 v[252:253], v[252:253], v[72:73]
	s_waitcnt lgkmcnt(4)
	v_mfma_f32_32x32x16_bf16 v[50:65], v[192:195], v[66:69], v[50:65]
	v_pk_add_f32 v[74:75], v[74:75], v[248:249] op_sel_hi:[1,0]
	v_pk_add_f32 v[76:77], v[76:77], v[248:249] op_sel_hi:[1,0]
	v_pk_add_f32 v[78:79], v[78:79], v[248:249] op_sel_hi:[1,0]
	v_pk_add_f32 v[80:81], v[80:81], v[248:249] op_sel_hi:[1,0]
	v_exp_f32_e32 v74, v74
	v_mfma_f32_32x32x16_bf16 v[34:49], v[202:205], v[66:69], v[34:49]
	v_exp_f32_e32 v75, v75
	v_exp_f32_e32 v76, v76
	v_exp_f32_e32 v77, v77
	v_exp_f32_e32 v78, v78
	v_exp_f32_e32 v79, v79
	v_mfma_f32_32x32x16_bf16 v[18:33], v[210:213], v[66:69], v[18:33]
	v_exp_f32_e32 v80, v80
	v_exp_f32_e32 v81, v81
	v_pk_add_f32 v[252:253], v[252:253], v[74:75]
	v_pk_add_f32 v[252:253], v[252:253], v[76:77]
	v_cvt_pk_bf16_f32 v74, v74, v75
	v_mfma_f32_32x32x16_bf16 v[2:17], v[218:221], v[66:69], v[2:17]
	v_cvt_pk_bf16_f32 v75, v76, v77
	v_cvt_pk_bf16_f32 v76, v78, v79
	v_cvt_pk_bf16_f32 v77, v80, v81
	v_pk_add_f32 v[252:253], v[252:253], v[78:79]
	v_pk_add_f32 v[252:253], v[252:253], v[80:81]
	s_waitcnt lgkmcnt(0)
	v_mfma_f32_32x32x16_bf16 v[50:65], v[196:199], v[74:77], v[50:65]
	v_add_f32_e32 v250, v252, v253
	v_mfma_f32_32x32x16_bf16 v[34:49], v[206:209], v[74:77], v[34:49]
	v_add_f32_e32 v191, v191, v250
	v_mfma_f32_32x32x16_bf16 v[18:33], v[214:217], v[74:77], v[18:33]
	v_mfma_f32_32x32x16_bf16 v[2:17], v[222:225], v[74:77], v[2:17]
.La_endA:
	ds_read_b128 v[192:195], v201 offset:32768
	ds_read_b128 v[202:205], v135 offset:32768
	ds_read_b128 v[210:213], v249 offset:32768
	ds_read_b128 v[218:221], v254 offset:32768
	ds_read_b128 v[196:199], v201 offset:40960
	ds_read_b128 v[206:209], v135 offset:40960
	ds_read_b128 v[214:217], v249 offset:40960
	ds_read_b128 v[222:225], v254 offset:40960
	s_add_i32 s5, s81, 3
	s_cmp_ge_u32 s5, s73
	s_cbranch_scc1 .La_qk_nodmaB
	s_add_i32 s5, s82, 0x18000
	s_and_b32 s5, s5, 0x18000
	s_add_i32 s5, s72, s5
	s_mov_b32 m0, s5
	s_waitcnt lgkmcnt(4)
	v_mfma_f32_32x32x16_bf16 v[82:97], v[192:195], v[98:101], v[226:241]
	global_load_lds_dwordx4 v[140:141], off
	s_add_i32 m0, s5, 0x400
	v_add_f32_e32 v250, 0xc2800000, v137
	v_add_f32_e32 v143, v133, v121
	v_mfma_f32_32x32x16_bf16 v[82:97], v[202:205], v[102:105], v[82:97]
	global_load_lds_dwordx4 v[138:139], off
	s_add_i32 m0, s5, 0x4000
	v_fma_f32 v251, v127, v250, v188
	v_fma_f32 v142, v127, v250, -v132
	v_mfma_f32_32x32x16_bf16 v[82:97], v[210:213], v[106:109], v[82:97]
	global_load_lds_dwordx4 v134, s[44:45]
	s_add_i32 m0, s5, 0x4400
	v_max_f32_e32 v143, 0xff7fffff, v143
	v_add_f32_e32 v248, v142, v188
	v_mfma_f32_32x32x16_bf16 v[82:97], v[218:221], v[110:113], v[82:97]
	global_load_lds_dwordx4 v136, s[44:45]
	v_fma_f32 v255, v188, -2.0, v255
	v_add_f32_e32 v243, 4.0, v143
	ds_read_b128 v[192:195], v244 offset:49152
	ds_read_b128 v[202:205], v244 offset:53248
	ds_read_b128 v[210:213], v244 offset:57344
	ds_read_b128 v[218:221], v244 offset:61440
	s_waitcnt lgkmcnt(4)
	v_mfma_f32_32x32x16_bf16 v[66:81], v[196:199], v[98:101], v[226:241]
	s_add_u32 s44, s44, 0xffffff80
	s_addc_u32 s45, s45, -1
	v_lshl_add_u64 v[138:139], v[138:139], 0, s[38:39]
	v_lshl_add_u64 v[140:141], v[140:141], 0, s[38:39]
	v_mfma_f32_32x32x16_bf16 v[66:81], v[206:209], v[102:105], v[66:81]
	v_max3_f32 v0, v82, v83, v84
	v_max3_f32 v0, v0, v85, v86
	v_max3_f32 v0, v0, v87, v88
	v_max3_f32 v0, v0, v89, v90
	v_pk_add_f32 v[82:83], v[82:83], v[142:143] op_sel_hi:[1,0]
	v_pk_add_f32 v[84:85], v[84:85], v[142:143] op_sel_hi:[1,0]
	v_mfma_f32_32x32x16_bf16 v[66:81], v[214:217], v[106:109], v[66:81]
	v_pk_add_f32 v[86:87], v[86:87], v[142:143] op_sel_hi:[1,0]
	v_pk_add_f32 v[88:89], v[88:89], v[142:143] op_sel_hi:[1,0]
	v_exp_f32_e32 v82, v82
	v_exp_f32_e32 v83, v83
	v_exp_f32_e32 v84, v84
	v_max3_f32 v0, v0, v91, v92
	v_mfma_f32_32x32x16_bf16 v[66:81], v[222:225], v[110:113], v[66:81]
	v_exp_f32_e32 v85, v85
	v_exp_f32_e32 v86, v86
	v_exp_f32_e32 v87, v87
	v_max3_f32 v0, v0, v93, v94
	v_exp_f32_e32 v88, v88
	v_exp_f32_e32 v89, v89
	v_max3_f32 v0, v0, v95, v96
	v_max_f32_e32 v0, v0, v97
	v_cmp_ge_f32_e32 vcc, v255, v243
; #define LAS __attribute__((address_space(3)))
; __device__ __forceinline__ unsigned cvtpk(float lo, float hi) { return pg8::cvt_pk_bf16(lo, hi); }
; __device__ __forceinline__ float ex2(float v) { return __builtin_amdgcn_exp2f(v); }
; #define MFMA32(a, b, c) __builtin_amdgcn_mfma_f32_32x32x16_bf16((a), (b), (c), 0, 0, 0)
; __device__ __forceinline__ void unit(LAS unsigned char* lds, bf16_t* P1, const bf16_t* vaT, int b, int h, int qblk, float lam, const float* subln_w, const float* khalf) {
;     ...
;         const float mn = fmaxf(m, mt); const float alpha = ex2(m - mn); m = mn;
;         const float c0 = tb0 - mn, c1 = tb1 - mn;
;         f32x2 ps2 = (f32x2){0.f, 0.f};
; #pragma unroll
;         for (int r = 0; r < 16; r += 2) { f32x2 a = (f32x2){S0[r], S0[r + 1]} + c0, bq = (f32x2){S1[r], S1[r + 1]} + c1;
;             a.x = ex2(a.x); a.y = ex2(a.y); bq.x = ex2(bq.x); bq.y = ex2(bq.y); S0[r] = a.x; S0[r + 1] = a.y; S1[r] = bq.x; S1[r + 1] = bq.y; ps2 = ps2 + a; ps2 = ps2 + bq; }
;         l = l * alpha + (ps2.x + ps2.y);
;         if (__any(alpha != 1.f)) {
; #pragma unroll
;             for (int d = 0; d < 4; ++d) O[d] = O[d] * alpha;
;         }
;         u32x4 pk[2][2];
; #pragma unroll
;         for (int s = 0; s < 2; ++s) {
;             pk[0][s] = (u32x4){cvtpk(S0[8 * s + 0], S0[8 * s + 1]), cvtpk(S0[8 * s + 2], S0[8 * s + 3]), cvtpk(S0[8 * s + 4], S0[8 * s + 5]), cvtpk(S0[8 * s + 6], S0[8 * s + 7])};
;             pk[1][s] = (u32x4){cvtpk(S1[8 * s + 0], S1[8 * s + 1]), cvtpk(S1[8 * s + 2], S1[8 * s + 3]), cvtpk(S1[8 * s + 4], S1[8 * s + 5]), cvtpk(S1[8 * s + 6], S1[8 * s + 7])};
;         }
; #pragma unroll
;         for (int d = 0; d < 4; ++d)
; #pragma unroll
;             for (int t2 = 0; t2 < 2; ++t2)
; #pragma unroll
;                 for (int s = 0; s < 2; ++s) {
;                     const bf16x8 vf = *(const LAS bf16x8*)(kb + voff[2 * t2 + s] + d * 32 * 128);
;                     O[d] = MFMA32(vf, __builtin_bit_cast(bf16x8, pk[t2][s]), O[d]);
;                 }
;         }
.La_qk_doneB:
	ds_read_b128 v[196:199], v245 offset:49152
	ds_read_b128 v[206:209], v245 offset:53248
	ds_read_b128 v[214:217], v245 offset:57344
	ds_read_b128 v[222:225], v245 offset:61440
	s_cbranch_vccz .La_maxB
.La_nomaxB:
	v_pk_add_f32 v[252:253], v[82:83], v[84:85]
	v_cvt_pk_bf16_f32 v82, v82, v83
	v_cvt_pk_bf16_f32 v83, v84, v85
	v_cvt_pk_bf16_f32 v84, v86, v87
	v_cvt_pk_bf16_f32 v85, v88, v89
	v_pk_add_f32 v[252:253], v[252:253], v[86:87]
	v_pk_add_f32 v[252:253], v[252:253], v[88:89]
	s_waitcnt lgkmcnt(4)
	v_mfma_f32_32x32x16_bf16 v[50:65], v[192:195], v[82:85], v[50:65]
	ds_read_b128 v[192:195], v246 offset:49152
	v_pk_add_f32 v[90:91], v[90:91], v[142:143] op_sel_hi:[1,0]
	v_pk_add_f32 v[92:93], v[92:93], v[142:143] op_sel_hi:[1,0]
	v_pk_add_f32 v[94:95], v[94:95], v[142:143] op_sel_hi:[1,0]
	v_pk_add_f32 v[96:97], v[96:97], v[142:143] op_sel_hi:[1,0]
	v_exp_f32_e32 v90, v90
	v_mfma_f32_32x32x16_bf16 v[34:49], v[202:205], v[82:85], v[34:49]
	ds_read_b128 v[202:205], v246 offset:53248
	v_exp_f32_e32 v91, v91
	v_exp_f32_e32 v92, v92
	v_exp_f32_e32 v93, v93
	v_exp_f32_e32 v94, v94
	v_exp_f32_e32 v95, v95
	v_mfma_f32_32x32x16_bf16 v[18:33], v[210:213], v[82:85], v[18:33]
	ds_read_b128 v[210:213], v246 offset:57344
	v_exp_f32_e32 v96, v96
	v_exp_f32_e32 v97, v97
	v_pk_add_f32 v[252:253], v[252:253], v[90:91]
	v_pk_add_f32 v[252:253], v[252:253], v[92:93]
	v_cvt_pk_bf16_f32 v90, v90, v91
	v_mfma_f32_32x32x16_bf16 v[2:17], v[218:221], v[82:85], v[2:17]
	ds_read_b128 v[218:221], v246 offset:61440
	v_cvt_pk_bf16_f32 v91, v92, v93
	v_cvt_pk_bf16_f32 v92, v94, v95
	v_cvt_pk_bf16_f32 v93, v96, v97
	v_pk_add_f32 v[252:253], v[252:253], v[94:95]
	v_pk_add_f32 v[252:253], v[252:253], v[96:97]
	s_waitcnt lgkmcnt(4)
	v_mfma_f32_32x32x16_bf16 v[50:65], v[196:199], v[90:93], v[50:65]
	ds_read_b128 v[196:199], v247 offset:49152
	v_pk_add_f32 v[66:67], v[66:67], v[248:249] op_sel_hi:[1,0]
	v_pk_add_f32 v[68:69], v[68:69], v[248:249] op_sel_hi:[1,0]
	v_pk_add_f32 v[70:71], v[70:71], v[248:249] op_sel_hi:[1,0]
	v_pk_add_f32 v[72:73], v[72:73], v[248:249] op_sel_hi:[1,0]
	v_exp_f32_e32 v66, v66
	v_mfma_f32_32x32x16_bf16 v[34:49], v[206:209], v[90:93], v[34:49]
	ds_read_b128 v[206:209], v247 offset:53248
	v_exp_f32_e32 v67, v67
	v_exp_f32_e32 v68, v68
	v_exp_f32_e32 v69, v69
	v_exp_f32_e32 v70, v70
	v_exp_f32_e32 v71, v71
	v_mfma_f32_32x32x16_bf16 v[18:33], v[214:217], v[90:93], v[18:33]
	ds_read_b128 v[214:217], v247 offset:57344
	v_exp_f32_e32 v72, v72
	v_exp_f32_e32 v73, v73
	v_pk_add_f32 v[252:253], v[252:253], v[66:67]
	v_pk_add_f32 v[252:253], v[252:253], v[68:69]
	v_cvt_pk_bf16_f32 v66, v66, v67
	v_mfma_f32_32x32x16_bf16 v[2:17], v[222:225], v[90:93], v[2:17]
	ds_read_b128 v[222:225], v247 offset:61440
	v_cvt_pk_bf16_f32 v67, v68, v69
	v_cvt_pk_bf16_f32 v68, v70, v71
	v_cvt_pk_bf16_f32 v69, v72, v73
	v_pk_add_f32 v[252:253], v[252:253], v[70:71]
	v_pk_add_f32 v[252:253], v[252:253], v[72:73]
	s_waitcnt lgkmcnt(4)
	v_mfma_f32_32x32x16_bf16 v[50:65], v[192:195], v[66:69], v[50:65]
	v_pk_add_f32 v[74:75], v[74:75], v[248:249] op_sel_hi:[1,0]
	v_pk_add_f32 v[76:77], v[76:77], v[248:249] op_sel_hi:[1,0]
	v_pk_add_f32 v[78:79], v[78:79], v[248:249] op_sel_hi:[1,0]
	v_pk_add_f32 v[80:81], v[80:81], v[248:249] op_sel_hi:[1,0]
	v_exp_f32_e32 v74, v74
	v_mfma_f32_32x32x16_bf16 v[34:49], v[202:205], v[66:69], v[34:49]
	v_exp_f32_e32 v75, v75
	v_exp_f32_e32 v76, v76
	v_exp_f32_e32 v77, v77
	v_exp_f32_e32 v78, v78
	v_exp_f32_e32 v79, v79
	v_mfma_f32_32x32x16_bf16 v[18:33], v[210:213], v[66:69], v[18:33]
	v_exp_f32_e32 v80, v80
	v_exp_f32_e32 v81, v81
	v_pk_add_f32 v[252:253], v[252:253], v[74:75]
	v_pk_add_f32 v[252:253], v[252:253], v[76:77]
	v_cvt_pk_bf16_f32 v74, v74, v75
	v_mfma_f32_32x32x16_bf16 v[2:17], v[218:221], v[66:69], v[2:17]
	v_cvt_pk_bf16_f32 v75, v76, v77
	v_cvt_pk_bf16_f32 v76, v78, v79
	v_cvt_pk_bf16_f32 v77, v80, v81
	v_pk_add_f32 v[252:253], v[252:253], v[78:79]
	v_pk_add_f32 v[252:253], v[252:253], v[80:81]
	s_waitcnt lgkmcnt(0)
	v_mfma_f32_32x32x16_bf16 v[50:65], v[196:199], v[74:77], v[50:65]
	v_add_f32_e32 v250, v252, v253
	v_mfma_f32_32x32x16_bf16 v[34:49], v[206:209], v[74:77], v[34:49]
	v_add_f32_e32 v191, v191, v250
	v_mfma_f32_32x32x16_bf16 v[18:33], v[214:217], v[74:77], v[18:33]
	v_mfma_f32_32x32x16_bf16 v[2:17], v[222:225], v[74:77], v[2:17]

; #define LAS __attribute__((address_space(3)))
; __device__ __forceinline__ int crow(int r, int hi) { return (r & 3) + 8 * (r >> 2) + 4 * hi; }
; __device__ __forceinline__ float ex2(float v) { return __builtin_amdgcn_exp2f(v); }
; #define MFMA32(a, b, c) __builtin_amdgcn_mfma_f32_32x32x16_bf16((a), (b), (c), 0, 0, 0)
; __device__ __forceinline__ void unit(LAS unsigned char* lds, bf16_t* P1, const bf16_t* vaT, int b, int h, int qblk, float lam, const float* subln_w, const float* khalf) {
;     ...
;         for (int ks = 0; ks < 4; ++ks) {
;             const bf16x8 a0 = *(const LAS bf16x8*)(kb + koff[ks]);
;             const bf16x8 a1 = *(const LAS bf16x8*)(kb + koff[ks] + 32 * 256);
;             S0 = MFMA32(a0, qf[ks], S0); S1 = MFMA32(a1, qf[ks], S1);
;         }
;         const int kv0 = 64 * j;
;         if (j >= NT - 2) {
; #pragma unroll
;             for (int r = 0; r < 16; ++r) { const int kv = kv0 + crow(r, hi); if (kv > qrow) S0[r] = -INFINITY; if (kv + 32 > qrow) S1[r] = -INFINITY; }
;         }
;         const float tb0 = sl2 * (float)(kv0 - qrow), tb1 = tb0 + sl2 * 32.f;
;         float mx0 = S0[0], mx1 = S1[0];
; #pragma unroll
;         for (int r = 1; r < 16; ++r) { mx0 = fmaxf(mx0, S0[r]); mx1 = fmaxf(mx1, S1[r]); }
;         float mt = fmaxf(mx0 + tb0, mx1 + tb1); mt = fmaxf(mt, __shfl_xor(mt, 32));
;         const bool skip = __all((mt < m - 24.f) || (mt == -INFINITY));
;         if (!skip) {
;         const float mn = fmaxf(m, mt); const float alpha = ex2(m - mn); m = mn;
.La_qk_nodmaB0:
	s_waitcnt lgkmcnt(4)
	v_mfma_f32_32x32x16_bf16 v[82:97], v[192:195], v[98:101], v[226:241]
	v_add_f32_e32 v250, 0xc2800000, v137
	v_add_f32_e32 v143, v133, v121
	v_mfma_f32_32x32x16_bf16 v[82:97], v[202:205], v[102:105], v[82:97]
	v_fma_f32 v251, v127, v250, v188
	v_fma_f32 v142, v127, v250, -v132
	v_mfma_f32_32x32x16_bf16 v[82:97], v[210:213], v[106:109], v[82:97]
	v_max_f32_e32 v143, 0xff7fffff, v143
	v_add_f32_e32 v248, v142, v188
	v_mfma_f32_32x32x16_bf16 v[82:97], v[218:221], v[110:113], v[82:97]
	ds_read_b128 v[192:195], v244 offset:49152
	ds_read_b128 v[202:205], v244 offset:53248
	ds_read_b128 v[210:213], v244 offset:57344
	ds_read_b128 v[218:221], v244 offset:61440
	s_waitcnt lgkmcnt(4)
	v_mfma_f32_32x32x16_bf16 v[66:81], v[196:199], v[98:101], v[226:241]
	v_mfma_f32_32x32x16_bf16 v[66:81], v[206:209], v[102:105], v[66:81]
	v_max3_f32 v0, v82, v83, v84
	v_max3_f32 v0, v0, v85, v86
	v_mfma_f32_32x32x16_bf16 v[66:81], v[214:217], v[106:109], v[66:81]
	v_max3_f32 v0, v0, v87, v88
	v_max3_f32 v0, v0, v89, v90
	v_max3_f32 v0, v0, v91, v92
	v_mfma_f32_32x32x16_bf16 v[66:81], v[222:225], v[110:113], v[66:81]
	v_max3_f32 v0, v0, v93, v94
	v_max3_f32 v0, v0, v95, v96
	v_max_f32_e32 v0, v0, v97
	s_branch .La_qk_doneB0
.La_qk_nodmaA:
	s_waitcnt lgkmcnt(4)
	v_mfma_f32_32x32x16_bf16 v[82:97], v[192:195], v[98:101], v[226:241]
	v_add_u32_e32 v244, s82, v168
	v_add_u32_e32 v245, s82, v169
	v_add_u32_e32 v246, s82, v170
	v_mfma_f32_32x32x16_bf16 v[82:97], v[202:205], v[102:105], v[82:97]
	v_add_u32_e32 v247, s82, v171
	v_add_f32_e32 v143, v133, v121
	v_fma_f32 v251, v127, v137, v188
	v_mfma_f32_32x32x16_bf16 v[82:97], v[210:213], v[106:109], v[82:97]
	v_fma_f32 v142, v127, v137, -v132
	v_max_f32_e32 v143, 0xff7fffff, v143
	v_add_f32_e32 v248, v142, v188
	v_mfma_f32_32x32x16_bf16 v[82:97], v[218:221], v[110:113], v[82:97]
	v_fma_f32 v255, v188, -2.0, v255
	v_add_f32_e32 v243, 4.0, v143
	ds_read_b128 v[192:195], v244 offset:16384
	ds_read_b128 v[202:205], v244 offset:20480
	ds_read_b128 v[210:213], v244 offset:24576
	ds_read_b128 v[218:221], v244 offset:28672
	s_waitcnt lgkmcnt(4)
	v_mfma_f32_32x32x16_bf16 v[66:81], v[196:199], v[98:101], v[226:241]
	v_mfma_f32_32x32x16_bf16 v[66:81], v[206:209], v[102:105], v[66:81]
	v_max3_f32 v0, v82, v83, v84
	v_max3_f32 v0, v0, v85, v86
	v_max3_f32 v0, v0, v87, v88
	v_max3_f32 v0, v0, v89, v90
	v_pk_add_f32 v[82:83], v[82:83], v[142:143] op_sel_hi:[1,0]
	v_pk_add_f32 v[84:85], v[84:85], v[142:143] op_sel_hi:[1,0]
	v_mfma_f32_32x32x16_bf16 v[66:81], v[214:217], v[106:109], v[66:81]
	v_pk_add_f32 v[86:87], v[86:87], v[142:143] op_sel_hi:[1,0]
	v_pk_add_f32 v[88:89], v[88:89], v[142:143] op_sel_hi:[1,0]
	v_exp_f32_e32 v82, v82
	v_exp_f32_e32 v83, v83
	v_exp_f32_e32 v84, v84
	v_max3_f32 v0, v0, v91, v92
	v_mfma_f32_32x32x16_bf16 v[66:81], v[222:225], v[110:113], v[66:81]
	v_exp_f32_e32 v85, v85
	v_exp_f32_e32 v86, v86
	v_exp_f32_e32 v87, v87
	v_max3_f32 v0, v0, v93, v94
	v_exp_f32_e32 v88, v88
	v_exp_f32_e32 v89, v89
	v_max3_f32 v0, v0, v95, v96
	v_max_f32_e32 v0, v0, v97
	v_cmp_ge_f32_e32 vcc, v255, v243
	s_branch .La_qk_doneA
.La_maxA:
	v_fmac_f32_e32 v0, v127, v137
	s_nop 1
	v_max3_f32 v120, v66, v67, v68
	v_max3_f32 v120, v120, v69, v70
	v_max3_f32 v120, v120, v71, v72
	v_max3_f32 v120, v120, v73, v74
	v_max3_f32 v120, v120, v75, v76
	v_max3_f32 v120, v120, v77, v78
	v_max3_f32 v120, v120, v79, v80
	v_max_f32_e32 v120, v120, v81
	v_add_f32_e32 v120, v251, v120
	v_max_f32_e32 v0, v0, v120
	v_mov_b32_e32 v120, v0
	s_nop 1
	v_permlane32_swap_b32_e32 v0, v120
	v_max_f32_e32 v0, v0, v120
	v_cmp_lt_f32_e32 vcc, v0, v143
	v_max_f32_e32 v133, v133, v0
	v_mov_b32_e32 v255, v0
	s_andn2_b64 s[2:3], exec, vcc
	s_cbranch_scc0 .La_endA
	s_branch .La_nomaxA
.La_qk_nodmaB:
	s_waitcnt lgkmcnt(4)
	v_mfma_f32_32x32x16_bf16 v[82:97], v[192:195], v[98:101], v[226:241]
	v_add_f32_e32 v250, 0xc2800000, v137
	v_add_f32_e32 v143, v133, v121
	v_mfma_f32_32x32x16_bf16 v[82:97], v[202:205], v[102:105], v[82:97]
	v_fma_f32 v251, v127, v250, v188
	v_fma_f32 v142, v127, v250, -v132
	v_mfma_f32_32x32x16_bf16 v[82:97], v[210:213], v[106:109], v[82:97]
	v_max_f32_e32 v143, 0xff7fffff, v143
	v_add_f32_e32 v248, v142, v188
	v_mfma_f32_32x32x16_bf16 v[82:97], v[218:221], v[110:113], v[82:97]
	v_fma_f32 v255, v188, -2.0, v255
	v_add_f32_e32 v243, 4.0, v143
	ds_read_b128 v[192:195], v244 offset:49152
	ds_read_b128 v[202:205], v244 offset:53248
	ds_read_b128 v[210:213], v244 offset:57344
	ds_read_b128 v[218:221], v244 offset:61440
	s_waitcnt lgkmcnt(4)
	v_mfma_f32_32x32x16_bf16 v[66:81], v[196:199], v[98:101], v[226:241]
	v_mfma_f32_32x32x16_bf16 v[66:81], v[206:209], v[102:105], v[66:81]
	v_max3_f32 v0, v82, v83, v84
	v_max3_f32 v0, v0, v85, v86
	v_max3_f32 v0, v0, v87, v88
	v_max3_f32 v0, v0, v89, v90
	v_pk_add_f32 v[82:83], v[82:83], v[142:143] op_sel_hi:[1,0]
	v_pk_add_f32 v[84:85], v[84:85], v[142:143] op_sel_hi:[1,0]
	v_mfma_f32_32x32x16_bf16 v[66:81], v[214:217], v[106:109], v[66:81]
	v_pk_add_f32 v[86:87], v[86:87], v[142:143] op_sel_hi:[1,0]
	v_pk_add_f32 v[88:89], v[88:89], v[142:143] op_sel_hi:[1,0]
	v_exp_f32_e32 v82, v82
	v_exp_f32_e32 v83, v83
	v_exp_f32_e32 v84, v84
	v_max3_f32 v0, v0, v91, v92
	v_mfma_f32_32x32x16_bf16 v[66:81], v[222:225], v[110:113], v[66:81]
	v_exp_f32_e32 v85, v85
	v_exp_f32_e32 v86, v86
	v_exp_f32_e32 v87, v87
	v_max3_f32 v0, v0, v93, v94
	v_exp_f32_e32 v88, v88
	v_exp_f32_e32 v89, v89
	v_max3_f32 v0, v0, v95, v96
	v_max_f32_e32 v0, v0, v97
	v_cmp_ge_f32_e32 vcc, v255, v243
	s_branch .La_qk_doneB
.La_maxB:
	v_fmac_f32_e32 v0, v127, v250
	s_nop 1
	v_max3_f32 v120, v66, v67, v68
	v_max3_f32 v120, v120, v69, v70
	v_max3_f32 v120, v120, v71, v72
	v_max3_f32 v120, v120, v73, v74
	v_max3_f32 v120, v120, v75, v76
	v_max3_f32 v120, v120, v77, v78
	v_max3_f32 v120, v120, v79, v80
	v_max_f32_e32 v120, v120, v81
	v_add_f32_e32 v120, v251, v120
	v_max_f32_e32 v0, v0, v120
	v_mov_b32_e32 v120, v0
	s_nop 1
	v_permlane32_swap_b32_e32 v0, v120
	v_max_f32_e32 v0, v0, v120
	v_cmp_lt_f32_e32 vcc, v0, v143
	v_max_f32_e32 v133, v133, v0
	v_mov_b32_e32 v255, v0
	s_andn2_b64 s[2:3], exec, vcc
	s_cbranch_scc0 .La_endB
	s_branch .La_nomaxB
